# P0 part rotation with the class taken per wave ((blockIdx + wave) % 3) so every CU has all three kinds of work in flight
# baseline (speedup 1.0000x reference)
.LBB0_10:
	s_or_b64 exec, exec, s[2:3]
	s_load_dwordx16 s[72:87], s[0:1], 0x40
	v_readlane_b32 s0, v254, 5
	s_lshr_b32 s89, s0, 6
	v_readlane_b32 s0, v254, 9
	v_readlane_b32 s1, v254, 10
	v_readlane_b32 s2, v254, 11
	v_readlane_b32 s3, v254, 12
	s_cmp_lt_i32 s0, 1
	s_cselect_b64 s[2:3], -1, 0
	s_cmp_gt_i32 s1, 0
	s_cselect_b64 s[0:1], -1, 0
	v_writelane_b32 v254, s2, 31
	s_and_b64 s[6:7], s[2:3], s[0:1]
	s_andn2_b64 vcc, exec, s[6:7]
	v_and_b32_e32 v227, 63, v226
	v_writelane_b32 v254, s3, 32
	s_cbranch_vccnz .LBB0_183
	s_add_i32 s99, s88, s89
	s_mul_hi_u32 s0, s99, 0x55555556
	s_mul_i32 s0, s0, 3
	s_sub_u32 s99, s99, s0
	s_cmp_eq_u32 s99, 0
	s_cbranch_scc1 .Lp0_front
	s_cmp_eq_u32 s99, 1
	s_cbranch_scc1 .LBB0_163
	s_mov_b32 s99, 3
	s_lshl_b32 s0, s88, 3
	s_add_i32 s8, s89, s0
	s_lshl_b32 s10, s90, 3
	s_branch .LBB0_158
